# NSA window edge tiles: per-element branchy mask chain of the first accumulator replaced by branch-free v_cmp/s_and/v_cndmask
# speedup vs baseline: 1.0010x; 1.0010x over previous
.Lwe_slow:
	s_cmp_lg_u32 s3, s13
	s_cselect_b64 s[4:5], -1, 0
	s_cmp_eq_u32 s1, s13
	s_cselect_b64 vcc, -1, 0
	v_cndmask_b32_e64 v216, v205, 0, s[4:5]
	v_cndmask_b32_e32 v217, 63, v193, vcc
	v_cmp_le_u32_e32 vcc, v216, v217
	v_cmp_gt_u32_e64 s[14:15], 64, v216
	s_and_b64 vcc, s[14:15], vcc
	s_cbranch_vccz .LBB0_1109
	v_cmp_eq_u32_e64 s[14:15], 63, v217
	s_and_b64 s[16:17], s[4:5], s[14:15]
	s_xor_b64 s[4:5], vcc, -1
	ds_read_b128 v[112:115], v131
	ds_read_b128 v[116:119], v131 offset:32
	s_or_b64 s[14:15], s[16:17], s[4:5]
	v_cndmask_b32_e64 v48, 0, 1, s[14:15]
	v_cmp_ne_u32_e64 s[14:15], 0, v48
	s_cmp_lg_u64 s[14:15], exec
	s_cselect_b64 s[18:19], -1, 0
	s_or_b64 s[16:17], s[16:17], s[18:19]
	v_cndmask_b32_e64 v48, v210, 0, s[16:17]
	v_pk_add_f32 v[62:63], v[46:47], v[48:49] op_sel_hi:[1,0]
	v_pk_add_f32 v[60:61], v[44:45], v[48:49] op_sel_hi:[1,0]
	v_pk_add_f32 v[58:59], v[42:43], v[48:49] op_sel_hi:[1,0]
	v_pk_add_f32 v[56:57], v[40:41], v[48:49] op_sel_hi:[1,0]
	v_pk_add_f32 v[54:55], v[38:39], v[48:49] op_sel_hi:[1,0]
	v_pk_add_f32 v[52:53], v[36:37], v[48:49] op_sel_hi:[1,0]
	v_pk_add_f32 v[50:51], v[34:35], v[48:49] op_sel_hi:[1,0]
	v_pk_add_f32 v[48:49], v[32:33], v[48:49] op_sel_hi:[1,0]
	s_cmp_eq_u64 s[14:15], exec
	s_waitcnt lgkmcnt(1)
	v_mfma_f32_32x32x16_bf16 v[64:79], v[112:115], v[80:83], v[48:63]
	ds_read_b128 v[112:115], v131 offset:4608
	ds_read_b128 v[120:123], v131 offset:4640
	s_waitcnt lgkmcnt(1)
	v_mfma_f32_32x32x16_bf16 v[48:63], v[112:115], v[80:83], v[48:63]
	v_mfma_f32_32x32x16_bf16 v[64:79], v[116:119], v[84:87], v[64:79]
	ds_read_b128 v[112:115], v131 offset:64
	ds_read_b128 v[116:119], v131 offset:96
	s_waitcnt lgkmcnt(2)
	v_mfma_f32_32x32x16_bf16 v[48:63], v[120:123], v[84:87], v[48:63]
	s_waitcnt lgkmcnt(1)
	v_mfma_f32_32x32x16_bf16 v[64:79], v[112:115], v[88:91], v[64:79]
	ds_read_b128 v[112:115], v131 offset:4672
	ds_read_b128 v[218:221], v131 offset:4704
	s_waitcnt lgkmcnt(1)
	v_mfma_f32_32x32x16_bf16 v[48:63], v[112:115], v[88:91], v[48:63]
	v_mfma_f32_32x32x16_bf16 v[64:79], v[116:119], v[92:95], v[64:79]
	ds_read_b64_tr_b16 v[120:121], v160 offset:18432
	ds_read_b64_tr_b16 v[122:123], v160 offset:19968
	ds_read_b64_tr_b16 v[114:115], v160 offset:20032
	ds_read_b64_tr_b16 v[112:113], v160 offset:18496
	ds_read_b64_tr_b16 v[124:125], v160 offset:21504
	ds_read_b64_tr_b16 v[126:127], v160 offset:23040
	ds_read_b64_tr_b16 v[118:119], v160 offset:23104
	ds_read_b64_tr_b16 v[116:117], v160 offset:21568
	s_waitcnt lgkmcnt(8)
	v_mfma_f32_32x32x16_bf16 v[48:63], v[218:221], v[92:95], v[48:63]
	s_cbranch_scc1 .LBB0_1106
	s_nop 7
	v_cmp_ge_u32_e64 s[14:15], v161, v216
	v_cmp_le_u32_e64 s[16:17], v161, v217
	s_and_b64 s[14:15], s[14:15], s[16:17]
	s_and_b64 s[14:15], s[14:15], vcc
	v_cndmask_b32_e64 v48, v210, v48, s[14:15]
	v_cmp_ge_u32_e64 s[14:15], v162, v216
	v_cmp_le_u32_e64 s[16:17], v162, v217
	s_and_b64 s[14:15], s[14:15], s[16:17]
	s_and_b64 s[14:15], s[14:15], vcc
	v_cndmask_b32_e64 v49, v210, v49, s[14:15]
	v_cmp_ge_u32_e64 s[14:15], v164, v216
	v_cmp_le_u32_e64 s[16:17], v164, v217
	s_and_b64 s[14:15], s[14:15], s[16:17]
	s_and_b64 s[14:15], s[14:15], vcc
	v_cndmask_b32_e64 v50, v210, v50, s[14:15]
	v_cmp_ge_u32_e64 s[14:15], v166, v216
	v_cmp_le_u32_e64 s[16:17], v166, v217
	s_and_b64 s[14:15], s[14:15], s[16:17]
	s_and_b64 s[14:15], s[14:15], vcc
	v_cndmask_b32_e64 v51, v210, v51, s[14:15]
	v_cmp_ge_u32_e64 s[14:15], v168, v216
	v_cmp_le_u32_e64 s[16:17], v168, v217
	s_and_b64 s[14:15], s[14:15], s[16:17]
	s_and_b64 s[14:15], s[14:15], vcc
	v_cndmask_b32_e64 v52, v210, v52, s[14:15]
	v_cmp_ge_u32_e64 s[14:15], v170, v216
	v_cmp_le_u32_e64 s[16:17], v170, v217
	s_and_b64 s[14:15], s[14:15], s[16:17]
	s_and_b64 s[14:15], s[14:15], vcc
	v_cndmask_b32_e64 v53, v210, v53, s[14:15]
	v_cmp_ge_u32_e64 s[14:15], v172, v216
	v_cmp_le_u32_e64 s[16:17], v172, v217
	s_and_b64 s[14:15], s[14:15], s[16:17]
	s_and_b64 s[14:15], s[14:15], vcc
	v_cndmask_b32_e64 v54, v210, v54, s[14:15]
	v_cmp_ge_u32_e64 s[14:15], v174, v216
	v_cmp_le_u32_e64 s[16:17], v174, v217
	s_and_b64 s[14:15], s[14:15], s[16:17]
	s_and_b64 s[14:15], s[14:15], vcc
	v_cndmask_b32_e64 v55, v210, v55, s[14:15]
	v_cmp_ge_u32_e64 s[14:15], v176, v216
	v_cmp_le_u32_e64 s[16:17], v176, v217
	s_and_b64 s[14:15], s[14:15], s[16:17]
	s_and_b64 s[14:15], s[14:15], vcc
	v_cndmask_b32_e64 v56, v210, v56, s[14:15]
	v_cmp_ge_u32_e64 s[14:15], v178, v216
	v_cmp_le_u32_e64 s[16:17], v178, v217
	s_and_b64 s[14:15], s[14:15], s[16:17]
	s_and_b64 s[14:15], s[14:15], vcc
	v_cndmask_b32_e64 v57, v210, v57, s[14:15]
	v_cmp_ge_u32_e64 s[14:15], v180, v216
	v_cmp_le_u32_e64 s[16:17], v180, v217
	s_and_b64 s[14:15], s[14:15], s[16:17]
	s_and_b64 s[14:15], s[14:15], vcc
	v_cndmask_b32_e64 v58, v210, v58, s[14:15]
	v_cmp_ge_u32_e64 s[14:15], v182, v216
	v_cmp_le_u32_e64 s[16:17], v182, v217
	s_and_b64 s[14:15], s[14:15], s[16:17]
	s_and_b64 s[14:15], s[14:15], vcc
	v_cndmask_b32_e64 v59, v210, v59, s[14:15]
	v_cmp_ge_u32_e64 s[14:15], v184, v216
	v_cmp_le_u32_e64 s[16:17], v184, v217
	s_and_b64 s[14:15], s[14:15], s[16:17]
	s_and_b64 s[14:15], s[14:15], vcc
	v_cndmask_b32_e64 v60, v210, v60, s[14:15]
	v_cmp_ge_u32_e64 s[14:15], v186, v216
	v_cmp_le_u32_e64 s[16:17], v186, v217
	s_and_b64 s[14:15], s[14:15], s[16:17]
	s_and_b64 s[14:15], s[14:15], vcc
	v_cndmask_b32_e64 v61, v210, v61, s[14:15]
	v_cmp_ge_u32_e64 s[14:15], v189, v216
	v_cmp_le_u32_e64 s[16:17], v189, v217
	s_and_b64 s[14:15], s[14:15], s[16:17]
	s_and_b64 s[14:15], s[14:15], vcc
	v_cndmask_b32_e64 v62, v210, v62, s[14:15]
.LBB0_1101:
	v_cmp_ge_u32_e64 s[74:75], v138, v216
	v_cmp_le_u32_e64 s[78:79], v138, v217
	v_cmp_ge_u32_e64 s[70:71], v204, v216
	v_cmp_lt_u32_e64 s[76:77], v138, v217
	v_cmp_ge_u32_e64 s[66:67], v163, v216
	v_cmp_le_u32_e64 s[72:73], v163, v217
	v_cmp_ge_u32_e64 s[62:63], v165, v216
	v_cmp_le_u32_e64 s[68:69], v165, v217
	v_cmp_ge_u32_e64 s[58:59], v167, v216
	v_cmp_le_u32_e64 s[64:65], v167, v217
	v_cmp_ge_u32_e64 s[54:55], v169, v216
	v_cmp_le_u32_e64 s[60:61], v169, v217
	v_cmp_ge_u32_e64 s[50:51], v171, v216
	v_cmp_le_u32_e64 s[56:57], v171, v217
	v_cmp_ge_u32_e64 s[46:47], v173, v216
	v_cmp_le_u32_e64 s[52:53], v173, v217
	v_cmp_ge_u32_e64 s[42:43], v175, v216
	v_cmp_le_u32_e64 s[48:49], v175, v217
	v_cmp_ge_u32_e64 s[38:39], v177, v216
	v_cmp_le_u32_e64 s[44:45], v177, v217
	v_cmp_ge_u32_e64 s[34:35], v179, v216
	v_cmp_le_u32_e64 s[40:41], v179, v217
	v_cmp_ge_u32_e64 s[28:29], v181, v216
	v_cmp_le_u32_e64 s[36:37], v181, v217
	v_cmp_ge_u32_e64 s[24:25], v183, v216
	v_cmp_le_u32_e64 s[30:31], v183, v217
	v_cmp_ge_u32_e64 s[20:21], v185, v216
	v_cmp_le_u32_e64 s[26:27], v185, v217
	v_cmp_ge_u32_e64 s[16:17], v187, v216
	v_cmp_le_u32_e64 s[22:23], v187, v217
	v_cmp_ge_u32_e64 s[14:15], v190, v216
	v_cmp_le_u32_e64 s[18:19], v190, v217
	v_cmp_ge_u32_e64 s[80:81], v191, v216
	v_cmp_le_u32_e64 s[88:89], v191, v217
	s_and_b64 s[80:81], s[80:81], s[88:89]
	s_and_b64 s[80:81], s[80:81], vcc
	v_cndmask_b32_e64 v63, v210, v63, s[80:81]
	s_and_b64 s[4:5], s[74:75], s[78:79]
	s_and_b64 s[74:75], vcc, s[4:5]
	s_and_b64 s[4:5], s[70:71], s[76:77]
	s_and_b64 s[70:71], vcc, s[4:5]
	s_and_b64 s[4:5], s[66:67], s[72:73]
	s_and_b64 s[66:67], vcc, s[4:5]
	s_and_b64 s[4:5], s[62:63], s[68:69]
	s_and_b64 s[62:63], vcc, s[4:5]
	s_and_b64 s[4:5], s[58:59], s[64:65]
	s_and_b64 s[58:59], vcc, s[4:5]
	s_and_b64 s[4:5], s[54:55], s[60:61]
	s_and_b64 s[54:55], vcc, s[4:5]
	s_and_b64 s[4:5], s[50:51], s[56:57]
	s_and_b64 s[50:51], vcc, s[4:5]
	s_and_b64 s[4:5], s[46:47], s[52:53]
	s_and_b64 s[46:47], vcc, s[4:5]
	s_and_b64 s[4:5], s[42:43], s[48:49]
	s_and_b64 s[42:43], vcc, s[4:5]
	s_and_b64 s[4:5], s[38:39], s[44:45]
	s_and_b64 s[38:39], vcc, s[4:5]
	s_and_b64 s[4:5], s[34:35], s[40:41]
	s_and_b64 s[34:35], vcc, s[4:5]
	s_and_b64 s[4:5], s[28:29], s[36:37]
	s_and_b64 s[28:29], vcc, s[4:5]
	s_and_b64 s[4:5], s[24:25], s[30:31]
	s_and_b64 s[24:25], vcc, s[4:5]
	s_and_b64 s[4:5], s[20:21], s[26:27]
	s_and_b64 s[20:21], vcc, s[4:5]
	s_and_b64 s[4:5], s[16:17], s[22:23]
	s_and_b64 s[16:17], vcc, s[4:5]
	s_and_b64 s[4:5], s[14:15], s[18:19]
	s_and_b64 vcc, vcc, s[4:5]
	v_cndmask_b32_e64 v64, v210, v64, s[74:75]
	v_cndmask_b32_e64 v65, v210, v65, s[70:71]
	v_cndmask_b32_e64 v66, v210, v66, s[66:67]
	v_cndmask_b32_e64 v67, v210, v67, s[62:63]
	v_cndmask_b32_e64 v68, v210, v68, s[58:59]
	v_cndmask_b32_e64 v69, v210, v69, s[54:55]
	v_cndmask_b32_e64 v70, v210, v70, s[50:51]
	v_cndmask_b32_e64 v71, v210, v71, s[46:47]
	v_cndmask_b32_e64 v72, v210, v72, s[42:43]
	v_cndmask_b32_e64 v73, v210, v73, s[38:39]
	v_cndmask_b32_e64 v74, v210, v74, s[34:35]
	v_cndmask_b32_e64 v75, v210, v75, s[28:29]
	v_cndmask_b32_e64 v76, v210, v76, s[24:25]
	v_cndmask_b32_e64 v77, v210, v77, s[20:21]
	v_cndmask_b32_e64 v78, v210, v78, s[16:17]
	v_cndmask_b32_e32 v79, v210, v79, vcc

.Lwo_slow:
	s_cmp_lg_u32 s2, s13
	s_cselect_b64 s[4:5], -1, 0
	s_cmp_eq_u32 s91, s13
	s_cselect_b64 vcc, -1, 0
	v_cndmask_b32_e64 v216, v205, 0, s[4:5]
	v_cndmask_b32_e32 v217, 63, v193, vcc
	v_cmp_le_u32_e32 vcc, v216, v217
	v_cmp_gt_u32_e64 s[14:15], 64, v216
	s_and_b64 vcc, s[14:15], vcc
	s_cbranch_vccz .LBB0_1182
	v_cmp_eq_u32_e64 s[14:15], 63, v217
	s_and_b64 s[16:17], s[4:5], s[14:15]
	s_xor_b64 s[4:5], vcc, -1
	ds_read_b128 v[112:115], v131 offset:9216
	ds_read_b128 v[116:119], v131 offset:9248
	s_or_b64 s[14:15], s[16:17], s[4:5]
	v_cndmask_b32_e64 v48, 0, 1, s[14:15]
	v_cmp_ne_u32_e64 s[14:15], 0, v48
	s_cmp_lg_u64 s[14:15], exec
	s_cselect_b64 s[18:19], -1, 0
	s_or_b64 s[16:17], s[16:17], s[18:19]
	v_cndmask_b32_e64 v48, v210, 0, s[16:17]
	v_pk_add_f32 v[62:63], v[46:47], v[48:49] op_sel_hi:[1,0]
	v_pk_add_f32 v[60:61], v[44:45], v[48:49] op_sel_hi:[1,0]
	v_pk_add_f32 v[58:59], v[42:43], v[48:49] op_sel_hi:[1,0]
	v_pk_add_f32 v[56:57], v[40:41], v[48:49] op_sel_hi:[1,0]
	v_pk_add_f32 v[54:55], v[38:39], v[48:49] op_sel_hi:[1,0]
	v_pk_add_f32 v[52:53], v[36:37], v[48:49] op_sel_hi:[1,0]
	v_pk_add_f32 v[50:51], v[34:35], v[48:49] op_sel_hi:[1,0]
	v_pk_add_f32 v[48:49], v[32:33], v[48:49] op_sel_hi:[1,0]
	s_cmp_eq_u64 s[14:15], exec
	s_waitcnt lgkmcnt(1)
	v_mfma_f32_32x32x16_bf16 v[64:79], v[112:115], v[80:83], v[48:63]
	ds_read_b128 v[112:115], v131 offset:13824
	ds_read_b128 v[120:123], v131 offset:13856
	s_waitcnt lgkmcnt(1)
	v_mfma_f32_32x32x16_bf16 v[48:63], v[112:115], v[80:83], v[48:63]
	v_mfma_f32_32x32x16_bf16 v[64:79], v[116:119], v[84:87], v[64:79]
	ds_read_b128 v[112:115], v131 offset:9280
	ds_read_b128 v[116:119], v131 offset:9312
	s_waitcnt lgkmcnt(2)
	v_mfma_f32_32x32x16_bf16 v[48:63], v[120:123], v[84:87], v[48:63]
	s_waitcnt lgkmcnt(1)
	v_mfma_f32_32x32x16_bf16 v[64:79], v[112:115], v[88:91], v[64:79]
	ds_read_b128 v[112:115], v131 offset:13888
	ds_read_b128 v[218:221], v131 offset:13920
	s_waitcnt lgkmcnt(1)
	v_mfma_f32_32x32x16_bf16 v[48:63], v[112:115], v[88:91], v[48:63]
	v_mfma_f32_32x32x16_bf16 v[64:79], v[116:119], v[92:95], v[64:79]
	ds_read_b64_tr_b16 v[120:121], v160 offset:30720
	ds_read_b64_tr_b16 v[122:123], v160 offset:32256
	ds_read_b64_tr_b16 v[114:115], v160 offset:32320
	ds_read_b64_tr_b16 v[112:113], v160 offset:30784
	ds_read_b64_tr_b16 v[124:125], v160 offset:33792
	ds_read_b64_tr_b16 v[126:127], v160 offset:35328
	ds_read_b64_tr_b16 v[118:119], v160 offset:35392
	ds_read_b64_tr_b16 v[116:117], v160 offset:33856
	s_waitcnt lgkmcnt(8)
	v_mfma_f32_32x32x16_bf16 v[48:63], v[218:221], v[92:95], v[48:63]
	s_cbranch_scc1 .LBB0_1179
	s_nop 7
	v_cmp_ge_u32_e64 s[14:15], v161, v216
	v_cmp_le_u32_e64 s[16:17], v161, v217
	s_and_b64 s[14:15], s[14:15], s[16:17]
	s_and_b64 s[14:15], s[14:15], vcc
	v_cndmask_b32_e64 v48, v210, v48, s[14:15]
	v_cmp_ge_u32_e64 s[14:15], v162, v216
	v_cmp_le_u32_e64 s[16:17], v162, v217
	s_and_b64 s[14:15], s[14:15], s[16:17]
	s_and_b64 s[14:15], s[14:15], vcc
	v_cndmask_b32_e64 v49, v210, v49, s[14:15]
	v_cmp_ge_u32_e64 s[14:15], v164, v216
	v_cmp_le_u32_e64 s[16:17], v164, v217
	s_and_b64 s[14:15], s[14:15], s[16:17]
	s_and_b64 s[14:15], s[14:15], vcc
	v_cndmask_b32_e64 v50, v210, v50, s[14:15]
	v_cmp_ge_u32_e64 s[14:15], v166, v216
	v_cmp_le_u32_e64 s[16:17], v166, v217
	s_and_b64 s[14:15], s[14:15], s[16:17]
	s_and_b64 s[14:15], s[14:15], vcc
	v_cndmask_b32_e64 v51, v210, v51, s[14:15]
	v_cmp_ge_u32_e64 s[14:15], v168, v216
	v_cmp_le_u32_e64 s[16:17], v168, v217
	s_and_b64 s[14:15], s[14:15], s[16:17]
	s_and_b64 s[14:15], s[14:15], vcc
	v_cndmask_b32_e64 v52, v210, v52, s[14:15]
	v_cmp_ge_u32_e64 s[14:15], v170, v216
	v_cmp_le_u32_e64 s[16:17], v170, v217
	s_and_b64 s[14:15], s[14:15], s[16:17]
	s_and_b64 s[14:15], s[14:15], vcc
	v_cndmask_b32_e64 v53, v210, v53, s[14:15]
	v_cmp_ge_u32_e64 s[14:15], v172, v216
	v_cmp_le_u32_e64 s[16:17], v172, v217
	s_and_b64 s[14:15], s[14:15], s[16:17]
	s_and_b64 s[14:15], s[14:15], vcc
	v_cndmask_b32_e64 v54, v210, v54, s[14:15]
	v_cmp_ge_u32_e64 s[14:15], v174, v216
	v_cmp_le_u32_e64 s[16:17], v174, v217
	s_and_b64 s[14:15], s[14:15], s[16:17]
	s_and_b64 s[14:15], s[14:15], vcc
	v_cndmask_b32_e64 v55, v210, v55, s[14:15]
	v_cmp_ge_u32_e64 s[14:15], v176, v216
	v_cmp_le_u32_e64 s[16:17], v176, v217
	s_and_b64 s[14:15], s[14:15], s[16:17]
	s_and_b64 s[14:15], s[14:15], vcc
	v_cndmask_b32_e64 v56, v210, v56, s[14:15]
	v_cmp_ge_u32_e64 s[14:15], v178, v216
	v_cmp_le_u32_e64 s[16:17], v178, v217
	s_and_b64 s[14:15], s[14:15], s[16:17]
	s_and_b64 s[14:15], s[14:15], vcc
	v_cndmask_b32_e64 v57, v210, v57, s[14:15]
	v_cmp_ge_u32_e64 s[14:15], v180, v216
	v_cmp_le_u32_e64 s[16:17], v180, v217
	s_and_b64 s[14:15], s[14:15], s[16:17]
	s_and_b64 s[14:15], s[14:15], vcc
	v_cndmask_b32_e64 v58, v210, v58, s[14:15]
	v_cmp_ge_u32_e64 s[14:15], v182, v216
	v_cmp_le_u32_e64 s[16:17], v182, v217
	s_and_b64 s[14:15], s[14:15], s[16:17]
	s_and_b64 s[14:15], s[14:15], vcc
	v_cndmask_b32_e64 v59, v210, v59, s[14:15]
	v_cmp_ge_u32_e64 s[14:15], v184, v216
	v_cmp_le_u32_e64 s[16:17], v184, v217
	s_and_b64 s[14:15], s[14:15], s[16:17]
	s_and_b64 s[14:15], s[14:15], vcc
	v_cndmask_b32_e64 v60, v210, v60, s[14:15]
	v_cmp_ge_u32_e64 s[14:15], v186, v216
	v_cmp_le_u32_e64 s[16:17], v186, v217
	s_and_b64 s[14:15], s[14:15], s[16:17]
	s_and_b64 s[14:15], s[14:15], vcc
	v_cndmask_b32_e64 v61, v210, v61, s[14:15]
	v_cmp_ge_u32_e64 s[14:15], v189, v216
	v_cmp_le_u32_e64 s[16:17], v189, v217
	s_and_b64 s[14:15], s[14:15], s[16:17]
	s_and_b64 s[14:15], s[14:15], vcc
	v_cndmask_b32_e64 v62, v210, v62, s[14:15]
